# FFN-up K-loop: one static s_setprio 1 for waves 4-7 before the loop, per-phase flips removed, reset at phase end
# baseline (speedup 1.0000x reference)
.LBB0_934:
	s_and_b64 vcc, exec, s[0:1]
	s_cbranch_vccz .LBB0_951
	s_cmpk_gt_i32 s9, 0xaff
	v_readfirstlane_b32 s1, v198
	s_cbranch_scc1 .LBB0_951
	v_lshlrev_b32_e32 v0, 4, v198
	s_waitcnt lgkmcnt(0)
	v_add_u32_e32 v1, 0x2000, v0
	v_ashrrev_i32_e32 v2, 31, v1
	v_lshrrev_b32_e32 v2, 22, v2
	v_add_u32_e32 v2, v1, v2
	v_ashrrev_i32_e32 v8, 10, v2
	v_mul_i32_i24_e32 v2, 0x400, v8
	v_sub_u32_e32 v1, v1, v2
	v_lshrrev_b32_e32 v2, 4, v1
	v_bitop3_b32 v1, v2, v1, 32 bitop3:0x6c
	v_ashrrev_i32_e32 v2, 31, v1
	v_lshrrev_b32_e32 v2, 26, v2
	v_readlane_b32 s0, v255, 32
	v_add_u32_e32 v2, v1, v2
	v_lshlrev_b32_e32 v3, 3, v8
	s_cmp_eq_u32 s0, 1
	v_ashrrev_i32_e32 v9, 6, v2
	v_and_b32_e32 v3, -16, v3
	s_cselect_b32 s0, 0, 0x2000000
	v_add_u32_e32 v3, v9, v3
	s_add_u32 s16, s91, s0
	v_and_b32_e32 v4, 3, v9
	s_mov_b32 s0, 0x1fffe0
	v_lshrrev_b32_e32 v5, 2, v3
	v_lshlrev_b32_e32 v6, 1, v3
	v_and_b32_e32 v2, 0xc0, v2
	v_and_or_b32 v4, v3, s0, v4
	v_and_b32_e32 v5, 4, v5
	v_and_b32_e32 v6, 24, v6
	v_sub_u32_e32 v1, v1, v2
	v_or3_b32 v4, v4, v5, v6
	v_lshlrev_b32_e32 v5, 5, v8
	v_ashrrev_i16_sdwa v1, v252, sext(v1) dst_sel:DWORD dst_unused:UNUSED_PAD src0_sel:DWORD src1_sel:BYTE_0
	v_and_b32_e32 v5, 32, v5
	v_bfe_i32 v10, v1, 0, 16
	v_add_lshl_u32 v1, v5, v10, 1
	v_lshl_add_u32 v154, v4, 11, v1
	v_lshl_add_u32 v156, v3, 11, v1
	v_bfe_i32 v1, v198, 27, 1
	v_lshrrev_b32_e32 v1, 22, v1
	v_add_u32_e32 v1, v0, v1
	v_and_b32_e32 v1, 0xfffffc00, v1
	v_sub_u32_e32 v0, v0, v1
	v_lshrrev_b32_e32 v1, 4, v0
	v_ashrrev_i32_e32 v2, 31, v198
	v_bitop3_b32 v0, v1, v0, 32 bitop3:0x6c
	v_lshrrev_b32_e32 v2, 26, v2
	v_ashrrev_i32_e32 v1, 31, v0
	v_add_u32_e32 v2, v198, v2
	v_lshrrev_b32_e32 v1, 26, v1
	v_ashrrev_i32_e32 v12, 6, v2
	v_add_u32_e32 v1, v0, v1
	v_lshlrev_b32_e32 v2, 3, v12
	v_ashrrev_i32_e32 v11, 6, v1
	v_and_b32_e32 v2, -16, v2
	s_addc_u32 s38, s90, 0
	v_add_u32_e32 v2, v11, v2
	v_and_b32_e32 v3, 3, v11
	s_ashr_i32 s45, s9, 31
	v_and_or_b32 v3, v2, s0, v3
	s_lshr_b32 s0, s45, 29
	s_add_i32 s0, s9, s0
	s_ashr_i32 s8, s1, 6
	s_ashr_i32 s4, s0, 3
	s_and_b32 s0, s0, -8
	s_ashr_i32 s2, s1, 8
	s_lshl_b32 s39, s8, 10
	s_sub_i32 s0, s9, s0
	s_cmp_lt_i32 s0, 0
	s_movk_i32 s5, 0x161
	s_cselect_b32 s5, s5, 0x160
	s_mul_i32 s0, s5, s0
	s_add_i32 s0, s0, s4
	s_mul_hi_i32 s4, s0, 0x2e8ba2e9
	s_lshr_b32 s5, s4, 31
	s_ashr_i32 s4, s4, 5
	s_add_i32 s4, s4, s5
	s_lshl_b32 s5, s4, 3
	s_mulk_i32 s4, 0xb0
	s_sub_i32 s4, s0, s4
	s_bfe_u32 s0, s4, 0x3001c
	s_add_i32 s6, s4, s0
	s_sext_i32_i16 s0, s6
	s_and_b32 s6, s6, 0xfff8
	s_sub_i32 s4, s4, s6
	s_sext_i32_i16 s4, s4
	v_lshrrev_b32_e32 v4, 2, v2
	v_lshlrev_b32_e32 v5, 1, v2
	v_and_b32_e32 v1, 0xc0, v1
	s_lshr_b32 s0, s0, 3
	s_add_i32 s4, s5, s4
	v_and_b32_e32 v4, 4, v4
	v_and_b32_e32 v5, 24, v5
	v_sub_u32_e32 v0, v0, v1
	s_ashr_i32 s5, s4, 31
	s_bfe_i64 s[14:15], s[0:1], 0x100000
	v_or3_b32 v3, v3, v4, v5
	v_lshlrev_b32_e32 v4, 5, v12
	v_ashrrev_i16_sdwa v0, v252, sext(v0) dst_sel:DWORD dst_unused:UNUSED_PAD src0_sel:DWORD src1_sel:BYTE_0
	s_lshl_b64 s[6:7], s[4:5], 19
	s_lshl_b64 s[14:15], s[14:15], 19
	v_and_b32_e32 v4, 32, v4
	v_bfe_i32 v13, v0, 0, 16
	s_add_u32 s66, s16, s14
	v_add_lshl_u32 v0, v4, v13, 1
	s_addc_u32 s67, s38, s15
	s_add_i32 s47, s39, 0
	v_lshl_add_u32 v96, v3, 11, v0
	s_add_i32 m0, s47, 0x10000
	v_lshl_add_u32 v158, v2, 11, v0
	global_load_lds_dwordx4 v96, s[66:67]
	s_add_i32 m0, s47, 0x12000
	s_add_u32 s14, s66, 0x40000
	global_load_lds_dwordx4 v154, s[66:67]
	s_addc_u32 s15, s67, 0
	s_add_i32 m0, s47, 0x14000
	v_mov_b32_e32 v155, v97
	global_load_lds_dwordx4 v96, s[14:15]
	s_add_i32 m0, s47, 0x16000
	s_add_u32 s42, s52, s6
	s_addc_u32 s43, s53, s7
	s_add_i32 s70, s47, 0x2000
	global_load_lds_dwordx4 v154, s[14:15]
	s_mov_b32 m0, s47
	s_add_u32 s6, s42, 0x40000
	global_load_lds_dwordx4 v158, s[42:43]
	s_mov_b32 m0, s70
	s_addc_u32 s7, s43, 0
	s_add_i32 s71, s47, 0x4000
	global_load_lds_dwordx4 v156, s[42:43]
	s_mov_b32 m0, s71
	s_add_i32 s72, s47, 0x6000
	global_load_lds_dwordx4 v158, s[6:7]
	s_mov_b32 m0, s72
	v_mov_b32_e32 v159, v97
	global_load_lds_dwordx4 v156, s[6:7]
	v_mov_b32_e32 v157, v97
	s_cmp_eq_u32 s2, 1
	v_lshl_add_u64 v[6:7], s[66:67], 0, v[96:97]
	v_lshl_add_u64 v[4:5], s[66:67], 0, v[154:155]
	v_lshl_add_u64 v[0:1], s[42:43], 0, v[158:159]
	s_cselect_b64 s[6:7], -1, 0
	s_cmp_lg_u32 s2, 1
	v_lshl_add_u64 v[2:3], s[42:43], 0, v[156:157]
	s_cbranch_scc1 .LBB0_938
	s_setprio 1
	s_barrier

.LBB0_951:
	s_setprio 0
	v_readlane_b32 s0, v255, 26
	v_readlane_b32 s1, v255, 27
	s_andn2_b64 vcc, exec, s[0:1]
	s_mov_b32 s35, 0x16000
	s_mov_b32 s54, 0xa000
	s_mov_b32 s55, 0xb000
	s_mov_b32 s56, 0x2a000
	s_mov_b32 s57, 0x2c000
	s_cbranch_vccnz .LBB0_957
	v_readlane_b32 s0, v255, 32
	s_cmp_eq_u32 s0, 0
	s_cbranch_scc0 .LBB0_957
	s_ashr_i32 s47, s46, 31
	s_lshl_b64 s[0:1], s[46:47], 9
	s_waitcnt lgkmcnt(0)
	v_mov_b64_e32 v[0:1], 0x1ffffff
	v_cmp_gt_u64_e32 vcc, s[0:1], v[0:1]
	s_cbranch_vccnz .LBB0_957
	s_ashr_i32 s45, s44, 31
	v_lshl_or_b32 v0, v246, 3, s0
	v_mov_b32_e32 v1, s1
	s_lshl_b64 s[0:1], s[44:45], 9
	s_lshl_b64 s[4:5], s[46:47], 11
	s_add_u32 s4, s50, s4
	v_lshlrev_b32_e32 v96, 5, v246
	s_addc_u32 s5, s51, s5
	v_lshl_add_u64 v[2:3], s[4:5], 0, v[96:97]
	s_lshl_b64 s[4:5], s[44:45], 11
	s_lshl_b64 s[6:7], s[46:47], 10
	s_add_u32 s6, s52, s6
	v_lshlrev_b32_e32 v96, 4, v246
	s_addc_u32 s7, s53, s7
	v_lshl_add_u64 v[2:3], v[2:3], 0, 16
	v_lshl_add_u64 v[4:5], s[6:7], 0, v[96:97]
	s_lshl_b64 s[24:25], s[44:45], 10
	s_mov_b64 s[6:7], 0
